# v91 + hgC first two queue ids drawn at P3 start (hidden under the scan)
# baseline (speedup 1.0000x reference)
; #define SEAM(k) do { if (IN(k) && IN((k) + 1)) { xcd_barrier(bar); if (F.bid == 0 && F.tid == 0) { const unsigned long long t_ = __builtin_amdgcn_s_memtime(); MISC[32 + 2 * ((k) + 1)] = (unsigned)t_; MISC[33 + 2 * ((k) + 1)] = (unsigned)(t_ >> 32); } } } while (0)
; #define SEAM(k) do { if (IN(k) && IN((k) + 1)) { xcd_barrier(bar); if (F.bid == 0 && F.tid == 0) { const unsigned long long t_ = __builtin_amdgcn_s_memrealtime(); MISC[32 + 2 * ((k) + 1)] = (unsigned)t_; MISC[33 + 2 * ((k) + 1)] = (unsigned)(t_ >> 32); } } } while (0)
; #define SEAM(k) do { if (IN(k) && IN((k) + 1)) { xcd_barrier(bar); xcd_barrier(bar); } } while (0)
; #define SEAM(k) do { if (IN(k) && IN((k) + 1)) xcd_barrier(bar); } while (0)
; #define SEAM(k) do { } while (0)
; __device__ __forceinline__ void hgC_loop(Frame& F, unsigned* ctr) {
;     ...
;     if (tid == 0) { slot[0] = (int)__hip_atomic_fetch_add(ctr, 1u, __ATOMIC_RELAXED, __HIP_MEMORY_SCOPE_AGENT); slot[1] = (int)__hip_atomic_fetch_add(ctr, 1u, __ATOMIC_RELAXED, __HIP_MEMORY_SCOPE_AGENT); }
; __global__ void __launch_bounds__(NWAVES * 64, 2) mk_fwd(Args args) {
;     ...
;     if (IN(3)) { hg_scan(F, (bf16*)(F.ws + WS_DSC), F.bid, F.G); } SEAM(3);
.LBB0_607:
	v_readlane_b32 s0, v238, 0
	v_readlane_b32 s1, v238, 1
	s_cmp_lt_i32 s0, 4
	s_cselect_b64 s[0:1], -1, 0
	s_and_b64 s[0:1], s[0:1], s[4:5]
	s_andn2_b64 vcc, exec, s[0:1]
	s_cbranch_vccnz .LBB0_611
	s_cmpk_gt_i32 s2, 0xff
	s_cbranch_scc1 .LBB0_611
	s_and_saveexec_b64 s[6:7], s[92:93]
	s_cbranch_execz my_hgq_early
	s_and_b32 s3, s2, 7
	s_lshl_b32 s3, s3, 8
	s_add_u32 s8, s50, 0x8000
	s_addc_u32 s9, s51, 0
	s_add_u32 s8, s8, s3
	s_addc_u32 s9, s9, 0
	v_mov_b32_e32 v2, 0
	v_mov_b32_e32 v3, 2
	global_atomic_add v236, v2, v3, s[8:9] sc0
my_hgq_early:
	s_or_b64 exec, exec, s[6:7]
	v_lshlrev_b32_e32 v2, 2, v0
	v_and_b32_e32 v6, 0x7c, v2
	v_lshlrev_b32_e32 v2, 1, v6
	v_mov_b32_e32 v3, 0
	v_lshl_add_u64 v[4:5], s[46:47], 0, v[2:3]
	v_lshlrev_b32_e32 v2, 9, v6
	v_lshlrev_b32_e32 v8, 4, v0
	v_lshl_add_u32 v71, v6, 2, 0
	v_lshl_add_u64 v[6:7], s[48:49], 0, v[2:3]
	s_mov_b64 s[4:5], 0x4420000
	v_mov_b32_e32 v9, v3
	v_add_u32_e32 v70, 0, v8
	v_lshl_add_u64 v[6:7], v[6:7], 0, s[4:5]
	v_lshl_add_u64 v[8:9], s[50:51], 0, v[8:9]
	s_mov_b64 s[4:5], 0x100000
	s_lshl_b32 s3, s2, 9
	s_lshl_b32 s8, s52, 9
	v_lshl_add_u64 v[8:9], v[8:9], 0, s[4:5]
	s_movk_i32 s9, 0x2000
	v_mov_b32_e32 v72, v3
	v_mov_b32_e32 v73, v3

; __device__ __forceinline__ void hgC_loop(Frame& F, unsigned* ctr) {
;     ...
;     if (tid == 0) { slot[0] = (int)__hip_atomic_fetch_add(ctr, 1u, __ATOMIC_RELAXED, __HIP_MEMORY_SCOPE_AGENT); slot[1] = (int)__hip_atomic_fetch_add(ctr, 1u, __ATOMIC_RELAXED, __HIP_MEMORY_SCOPE_AGENT); }
;     __syncthreads();
;     int item = slot[0], nxt = slot[1], par = 0;
;     if (item >= 1024) return;
.LBB0_684:
	s_add_u32 s4, s50, 0x8000
	s_addc_u32 s5, s51, 0
	s_and_b32 s3, s2, 7
	s_lshl_b32 s30, s3, 7
	s_lshl_b32 s3, s3, 8
	s_add_u32 s4, s4, s3
	s_addc_u32 s5, s5, 0
	v_mov_b32_e32 v235, 0x400
	s_waitcnt vmcnt(0)
	s_barrier
	s_and_saveexec_b64 s[0:1], s[92:93]
	s_cbranch_execz .LBB0_690
	v_mov_b32_e32 v2, 0
	v_mov_b32_e32 v4, 2
	v_mov_b32_e32 v3, v236
	v_add_u32_e32 v4, 1, v3
	v_cmp_gt_u32_e32 vcc, 0x80, v3
	v_add_u32_e32 v3, s30, v3
	s_nop 1
	v_cndmask_b32_e32 v3, v235, v3, vcc
	ds_write_b32 v2, v3 offset:53248
	v_cmp_gt_u32_e32 vcc, 0x80, v4
	v_add_u32_e32 v4, s30, v4
	s_nop 1
	v_cndmask_b32_e32 v4, v235, v4, vcc
	ds_write_b32 v2, v4 offset:53252
